# in-proj column-tile permutation: the tiles with the heavy QK-norm / f32 epilogues are spread evenly over the CUs instead of up to 3 of 4 on even-XCD CUs
# speedup vs baseline: 1.0165x; 1.0031x over previous
.LBB0_124:
	s_add_i32 s61, s61, 1
	v_readlane_b32 s4, v252, 54
	s_mul_i32 s4, s61, s4
	s_mul_hi_u32 s5, s61, s3
	s_add_i32 s5, s5, s4
	s_mul_i32 s4, s61, s3
	v_readlane_b32 s39, v252, 0
	s_add_u32 s42, s4, s39
	v_readlane_b32 s4, v252, 53
	s_addc_u32 s43, s5, s4
	v_mov_b64_e32 v[2:3], 0x3c0
	v_cmp_lt_i64_e64 s[4:5], s[42:43], v[2:3]
	v_mov_b64_e32 v[2:3], 0x3bf
	v_cmp_gt_i64_e32 vcc, s[42:43], v[2:3]
	s_cbranch_vccnz .LBB0_126
	s_ashr_i32 s38, s42, 31
	s_lshr_b32 s38, s38, 29
	s_add_i32 s38, s42, s38
	s_ashr_i32 s39, s38, 3
	s_and_b32 s38, s38, -8
	s_sub_i32 s38, s42, s38
	s_cmp_lt_i32 s38, 0
	s_movk_i32 s40, 0x79
	s_cselect_b32 s40, s40, 0x78
	s_mul_i32 s38, s38, s40
	s_add_i32 s38, s38, s39
	s_mul_hi_i32 s39, s38, 0x88888889
	s_add_i32 s39, s39, s38
	s_lshr_b32 s40, s39, 31
	s_ashr_i32 s39, s39, 7
	s_add_i32 s39, s39, s40
	s_lshl_b32 s40, s39, 3
	s_sub_i32 s41, 32, s40
	s_min_i32 s41, s41, 8
	s_abs_i32 s42, s41
	v_cvt_f32_u32_e32 v2, s42
	s_sub_i32 s44, 0, s42
	s_mulk_i32 s39, 0xf0
	s_sub_i32 s39, s38, s39
	v_rcp_iflag_f32_e32 v2, v2
	s_abs_i32 s38, s39
	s_xor_b32 s43, s39, s41
	s_ashr_i32 s43, s43, 31
	v_mul_f32_e32 v2, 0x4f7ffffe, v2
	v_cvt_u32_f32_e32 v2, v2
	s_nop 0
	v_readfirstlane_b32 s45, v2
	s_mul_i32 s44, s44, s45
	s_mul_hi_u32 s44, s45, s44
	s_add_i32 s45, s45, s44
	s_mul_hi_u32 s44, s38, s45
	s_mul_i32 s45, s44, s42
	s_sub_i32 s38, s38, s45
	s_add_i32 s50, s44, 1
	s_sub_i32 s45, s38, s42
	s_cmp_ge_u32 s38, s42
	s_cselect_b32 s44, s50, s44
	s_cselect_b32 s38, s45, s38
	s_add_i32 s45, s44, 1
	s_cmp_ge_u32 s38, s42
	s_cselect_b32 s38, s45, s44
	s_xor_b32 s38, s38, s43
	s_sub_i32 s38, s38, s43
	s_mul_i32 s41, s38, s41
	s_sub_i32 s39, s39, s41
	s_add_i32 s40, s40, s39
	s_mul_i32 s41, s38, 43
	s_lshr_b32 s41, s41, 8
	s_mul_i32 s44, s41, 6
	s_sub_i32 s44, s38, s44
	s_mul_i32 s44, s44, 5
	s_mov_b32 s45, 0xa418820
	s_cmp_eq_u32 s41, 1
	s_cselect_b32 s45, 0x2ab41a8a, s45
	s_cmp_eq_u32 s41, 2
	s_cselect_b32 s45, 0x2307cd27, s45
	s_cmp_eq_u32 s41, 3
	s_cselect_b32 s45, 0x2fb732d2, s45
	s_cmp_eq_u32 s41, 4
	s_cselect_b32 s45, 0x3b9c734d, s45
	s_lshr_b32 s45, s45, s44
	s_and_b32 s38, s45, 31
